# stack2: + attention epilogue gate loads hoisted (all 16 up front, counted waits) on all items, removed stale vmcnt(12) in attention prologues
# baseline (speedup 1.0000x reference)
.LBB0_320:
	s_and_b32 s35, s31, 3
	s_lshl_b32 s36, s35, 8
	v_readlane_b32 s4, v254, 22
	s_sub_i32 s64, s4, s36
	v_mbcnt_lo_u32_b32 v11, -1, 0
	v_mbcnt_hi_u32_b32 v11, -1, v11
	s_add_i32 s28, s64, 0x710
	v_and_b32_e32 v167, 31, v11
	v_add_u32_e32 v166, s28, v167
	v_min_i32_e32 v2, 0x80f, v166
	s_lshr_b32 s12, s31, 5
	v_ashrrev_i32_e32 v3, 31, v2
	v_mov_b32_e32 v16, 0x810
	v_mad_u64_u32 v[2:3], s[4:5], s12, v16, v[2:3]
	v_mov_b64_e32 v[4:5], s[50:51]
	s_bfe_u32 s6, s31, 0x30002
	v_mad_u64_u32 v[4:5], s[4:5], v2, s58, v[4:5]
	s_mul_i32 s4, s6, 0xc0
	v_bfe_u32 v10, v11, 5, 1
	v_mad_i32_i24 v5, v3, s58, v5
	s_lshl_b32 s14, s4, 1
	s_mov_b32 s15, s45
	v_lshl_add_u64 v[4:5], v[4:5], 0, s[14:15]
	s_waitcnt lgkmcnt(0)
	v_lshlrev_b32_e32 v0, 4, v10
	v_lshl_add_u64 v[4:5], v[4:5], 0, v[0:1]
	v_readlane_b32 s4, v253, 15
	global_load_dwordx4 v[98:101], v[4:5], off
	global_load_dwordx4 v[102:105], v[4:5], off offset:32
	global_load_dwordx4 v[106:109], v[4:5], off offset:64
	global_load_dwordx4 v[110:113], v[4:5], off offset:96
	global_load_dwordx4 v[114:117], v[4:5], off offset:128
	global_load_dwordx4 v[118:121], v[4:5], off offset:160
	global_load_dwordx4 v[122:125], v[4:5], off offset:192
	global_load_dwordx4 v[126:129], v[4:5], off offset:224
	global_load_dwordx4 v[130:133], v[4:5], off offset:256
	global_load_dwordx4 v[134:137], v[4:5], off offset:288
	global_load_dwordx4 v[138:141], v[4:5], off offset:320
	global_load_dwordx4 v[142:145], v[4:5], off offset:352
	v_add_u32_e32 v4, s4, v11
	v_readlane_b32 s4, v254, 48
	v_lshlrev_b64 v[2:3], 5, v[2:3]
	v_readlane_b32 s5, v254, 49
	s_lshl_b32 s44, s6, 2
	v_lshlrev_b32_e32 v5, 4, v4
	v_lshl_add_u64 v[2:3], s[4:5], 0, v[2:3]
	v_lshl_add_u64 v[6:7], v[2:3], 0, s[44:45]
	v_ashrrev_i32_e32 v2, 4, v4
	v_ashrrev_i32_e32 v3, 31, v2
	v_mad_u64_u32 v[8:9], s[4:5], s12, v16, v[2:3]
	v_lshlrev_b64 v[8:9], 11, v[8:9]
	v_lshl_add_u64 v[8:9], s[66:67], 0, v[8:9]
	s_lshl_b32 s4, s6, 8
	s_mov_b32 s5, s45
	v_lshl_add_u64 v[8:9], v[8:9], 0, s[4:5]
	v_and_b32_e32 v168, 0xf0, v5
	v_mov_b32_e32 v169, v1
	v_add_u32_e32 v13, 0x200, v4
	v_lshl_add_u64 v[8:9], v[8:9], 0, v[168:169]
	global_load_dword v12, v[6:7], off
	global_load_dwordx4 v[146:149], v[8:9], off
	v_ashrrev_i32_e32 v6, 4, v13
	v_ashrrev_i32_e32 v7, 31, v6
	s_lshl_b32 s34, s6, 7
	v_mad_u64_u32 v[8:9], s[6:7], s12, v16, v[6:7]
	v_lshlrev_b64 v[8:9], 11, v[8:9]
	v_lshl_add_u64 v[8:9], s[66:67], 0, v[8:9]
	v_lshl_add_u64 v[8:9], v[8:9], 0, s[4:5]
	v_lshl_add_u64 v[14:15], v[8:9], 0, v[168:169]
	v_ashrrev_i32_e32 v8, 3, v4
	v_ashrrev_i32_e32 v9, 31, v8
	v_mad_u64_u32 v[16:17], s[4:5], s12, v16, v[8:9]
	v_readlane_b32 s4, v254, 24
	v_lshlrev_b64 v[16:17], 7, v[16:17]
	v_readlane_b32 s5, v254, 25
	v_and_b32_e32 v170, 0x70, v5
	v_mov_b32_e32 v171, v1
	v_lshl_add_u64 v[16:17], s[4:5], 0, v[16:17]
	v_readlane_b32 s4, v254, 26
	v_readlane_b32 s5, v254, 27
	s_mul_hi_u32 s11, s12, 0x810
	s_mul_i32 s10, s12, 0x810
	v_lshl_add_u64 v[16:17], v[16:17], 0, v[170:171]
	global_load_dwordx4 v[150:153], v[14:15], off
	global_load_dwordx4 v[154:157], v[16:17], off
	v_add_u32_e32 v5, s34, v8
	v_mov_b64_e32 v[14:15], s[4:5]
	v_ashrrev_i32_e32 v13, 3, v13
	v_mad_i64_i32 v[16:17], s[4:5], v5, s85, v[14:15]
	s_lshl_b64 s[12:13], s[10:11], 1
	v_add_u32_e32 v5, s34, v13
	v_lshl_add_u64 v[16:17], v[16:17], 0, s[12:13]
	v_mad_i64_i32 v[14:15], s[4:5], v5, s85, v[14:15]
	v_lshl_add_u64 v[16:17], v[16:17], 0, v[170:171]
	v_lshl_add_u64 v[14:15], v[14:15], 0, s[12:13]
	v_lshl_add_u64 v[14:15], v[14:15], 0, v[170:171]
	global_load_dwordx4 v[158:161], v[16:17], off
	global_load_dwordx4 v[162:165], v[14:15], off
	v_cmp_lt_i32_e32 vcc, 63, v4
	v_cmp_gt_i32_e64 s[6:7], 64, v4
	v_mov_b32_e32 v169, 0
	v_ashrrev_i32_e32 v5, 31, v4
	v_mov_b32_e32 v171, 0
	s_and_saveexec_b64 s[4:5], s[6:7]
	s_cbranch_execz .LBB0_322
	v_readlane_b32 s16, v254, 28
	v_lshl_add_u64 v[14:15], s[10:11], 0, v[4:5]
	v_readlane_b32 s17, v254, 29
	s_nop 1
	v_lshl_add_u64 v[16:17], v[14:15], 2, s[16:17]
	v_readlane_b32 s16, v254, 52
	v_lshlrev_b64 v[14:15], 5, v[14:15]
	v_readlane_b32 s17, v254, 53
	s_nop 1
	v_lshl_add_u64 v[14:15], s[16:17], 0, v[14:15]
	v_lshl_add_u64 v[14:15], v[14:15], 0, s[44:45]
	global_load_dword v171, v[14:15], off
	global_load_dword v169, v[16:17], off

.LBB0_344:
	s_and_b64 vcc, exec, s[94:95]
	s_cbranch_vccz .LBB0_348
	ds_bpermute_b32 v0, v211, v216
	v_readlane_b32 s6, v254, 22
	s_nop 1
	v_or_b32_e32 v66, s6, v167
	s_movk_i32 s6, 0x100
	v_cmp_gt_i32_e32 vcc, s6, v66
	s_and_b64 s[16:17], s[2:3], vcc
	s_and_saveexec_b64 s[6:7], s[16:17]
	s_cbranch_execz .LBB0_347
	s_waitcnt lgkmcnt(0)
	v_add_f32_e32 v0, v216, v0
	v_div_scale_f32 v66, s[16:17], v0, v0, 1.0
	v_rcp_f32_e32 v67, v66
	v_ashrrev_i32_e32 v167, 31, v166
	v_readlane_b32 s16, v252, 43
	v_readlane_b32 s17, v252, 44
	v_fma_f32 v68, -v66, v67, 1.0
	v_fmac_f32_e32 v67, v68, v67
	v_div_scale_f32 v68, vcc, 1.0, v0, 1.0
	v_mul_f32_e32 v69, v68, v67
	v_fma_f32 v70, -v66, v69, v68
	v_fmac_f32_e32 v69, v70, v67
	v_fma_f32 v66, -v66, v69, v68
	v_div_fmas_f32 v66, v66, v67, v69
	v_lshl_add_u64 v[68:69], s[10:11], 0, v[166:167]
	v_lshlrev_b64 v[68:69], 11, v[68:69]
	v_lshl_add_u64 v[68:69], s[16:17], 0, v[68:69]
	s_lshl_b32 s16, s34, 1
	s_mov_b32 s17, s45
	v_div_fixup_f32 v66, v66, v0, 1.0
	v_lshl_add_u64 v[68:69], v[68:69], 0, s[16:17]
	v_lshlrev_b32_e32 v0, 1, v208
	v_lshl_add_u64 v[68:69], v[68:69], 0, v[0:1]
	global_load_dwordx2 v[98:99], v[68:69], off
	global_load_dwordx2 v[100:101], v[68:69], off offset:16
	global_load_dwordx2 v[102:103], v[68:69], off offset:32
	global_load_dwordx2 v[104:105], v[68:69], off offset:48
	global_load_dwordx2 v[106:107], v[68:69], off offset:64
	global_load_dwordx2 v[108:109], v[68:69], off offset:80
	global_load_dwordx2 v[110:111], v[68:69], off offset:96
	global_load_dwordx2 v[112:113], v[68:69], off offset:112
	global_load_dwordx2 v[114:115], v[68:69], off offset:128
	global_load_dwordx2 v[116:117], v[68:69], off offset:144
	global_load_dwordx2 v[118:119], v[68:69], off offset:160
	global_load_dwordx2 v[120:121], v[68:69], off offset:176
	global_load_dwordx2 v[122:123], v[68:69], off offset:192
	global_load_dwordx2 v[124:125], v[68:69], off offset:208
	global_load_dwordx2 v[126:127], v[68:69], off offset:224
	global_load_dwordx2 v[128:129], v[68:69], off offset:240
	s_waitcnt vmcnt(15)
	v_lshlrev_b32_e32 v130, 16, v98
	v_and_b32_e32 v131, 0xffff0000, v98
	v_lshlrev_b32_e32 v132, 16, v99
	v_and_b32_e32 v133, 0xffff0000, v99
	v_mul_f32_e32 v50, v66, v50
	v_mul_f32_e32 v51, v66, v51
	v_mul_f32_e32 v52, v66, v52
	v_mul_f32_e32 v53, v66, v53
	v_mul_f32_e32 v50, v50, v130
	v_mul_f32_e32 v51, v51, v131
	v_mul_f32_e32 v52, v52, v132
	v_mul_f32_e32 v53, v53, v133
	v_cvt_pk_bf16_f32 v50, v50, v51
	v_cvt_pk_bf16_f32 v51, v52, v53
	global_store_dwordx2 v[68:69], v[50:51], off
	s_waitcnt vmcnt(15)
	v_lshlrev_b32_e32 v130, 16, v100
	v_and_b32_e32 v131, 0xffff0000, v100
	v_lshlrev_b32_e32 v132, 16, v101
	v_and_b32_e32 v133, 0xffff0000, v101
	v_mul_f32_e32 v54, v66, v54
	v_mul_f32_e32 v55, v66, v55
	v_mul_f32_e32 v56, v66, v56
	v_mul_f32_e32 v57, v66, v57
	v_mul_f32_e32 v54, v54, v130
	v_mul_f32_e32 v55, v55, v131
	v_mul_f32_e32 v56, v56, v132
	v_mul_f32_e32 v57, v57, v133
	v_cvt_pk_bf16_f32 v54, v54, v55
	v_cvt_pk_bf16_f32 v55, v56, v57
	global_store_dwordx2 v[68:69], v[54:55], off offset:16
	s_waitcnt vmcnt(15)
	v_lshlrev_b32_e32 v130, 16, v102
	v_and_b32_e32 v131, 0xffff0000, v102
	v_lshlrev_b32_e32 v132, 16, v103
	v_and_b32_e32 v133, 0xffff0000, v103
	v_mul_f32_e32 v58, v66, v58
	v_mul_f32_e32 v59, v66, v59
	v_mul_f32_e32 v60, v66, v60
	v_mul_f32_e32 v61, v66, v61
	v_mul_f32_e32 v58, v58, v130
	v_mul_f32_e32 v59, v59, v131
	v_mul_f32_e32 v60, v60, v132
	v_mul_f32_e32 v61, v61, v133
	v_cvt_pk_bf16_f32 v58, v58, v59
	v_cvt_pk_bf16_f32 v59, v60, v61
	global_store_dwordx2 v[68:69], v[58:59], off offset:32
	s_waitcnt vmcnt(15)
	v_lshlrev_b32_e32 v130, 16, v104
	v_and_b32_e32 v131, 0xffff0000, v104
	v_lshlrev_b32_e32 v132, 16, v105
	v_and_b32_e32 v133, 0xffff0000, v105
	v_mul_f32_e32 v62, v66, v62
	v_mul_f32_e32 v63, v66, v63
	v_mul_f32_e32 v64, v66, v64
	v_mul_f32_e32 v65, v66, v65
	v_mul_f32_e32 v62, v62, v130
	v_mul_f32_e32 v63, v63, v131
	v_mul_f32_e32 v64, v64, v132
	v_mul_f32_e32 v65, v65, v133
	v_cvt_pk_bf16_f32 v62, v62, v63
	v_cvt_pk_bf16_f32 v63, v64, v65
	global_store_dwordx2 v[68:69], v[62:63], off offset:48
	s_waitcnt vmcnt(15)
	v_lshlrev_b32_e32 v130, 16, v106
	v_and_b32_e32 v131, 0xffff0000, v106
	v_lshlrev_b32_e32 v132, 16, v107
	v_and_b32_e32 v133, 0xffff0000, v107
	v_mul_f32_e32 v34, v66, v34
	v_mul_f32_e32 v35, v66, v35
	v_mul_f32_e32 v36, v66, v36
	v_mul_f32_e32 v37, v66, v37
	v_mul_f32_e32 v34, v34, v130
	v_mul_f32_e32 v35, v35, v131
	v_mul_f32_e32 v36, v36, v132
	v_mul_f32_e32 v37, v37, v133
	v_cvt_pk_bf16_f32 v34, v34, v35
	v_cvt_pk_bf16_f32 v35, v36, v37
	global_store_dwordx2 v[68:69], v[34:35], off offset:64
	s_waitcnt vmcnt(15)
	v_lshlrev_b32_e32 v130, 16, v108
	v_and_b32_e32 v131, 0xffff0000, v108
	v_lshlrev_b32_e32 v132, 16, v109
	v_and_b32_e32 v133, 0xffff0000, v109
	v_mul_f32_e32 v38, v66, v38
	v_mul_f32_e32 v39, v66, v39
	v_mul_f32_e32 v40, v66, v40
	v_mul_f32_e32 v41, v66, v41
	v_mul_f32_e32 v38, v38, v130
	v_mul_f32_e32 v39, v39, v131
	v_mul_f32_e32 v40, v40, v132
	v_mul_f32_e32 v41, v41, v133
	v_cvt_pk_bf16_f32 v38, v38, v39
	v_cvt_pk_bf16_f32 v39, v40, v41
	global_store_dwordx2 v[68:69], v[38:39], off offset:80
	s_waitcnt vmcnt(15)
	v_lshlrev_b32_e32 v130, 16, v110
	v_and_b32_e32 v131, 0xffff0000, v110
	v_lshlrev_b32_e32 v132, 16, v111
	v_and_b32_e32 v133, 0xffff0000, v111
	v_mul_f32_e32 v42, v66, v42
	v_mul_f32_e32 v43, v66, v43
	v_mul_f32_e32 v44, v66, v44
	v_mul_f32_e32 v45, v66, v45
	v_mul_f32_e32 v42, v42, v130
	v_mul_f32_e32 v43, v43, v131
	v_mul_f32_e32 v44, v44, v132
	v_mul_f32_e32 v45, v45, v133
	v_cvt_pk_bf16_f32 v42, v42, v43
	v_cvt_pk_bf16_f32 v43, v44, v45
	global_store_dwordx2 v[68:69], v[42:43], off offset:96
	s_waitcnt vmcnt(15)
	v_lshlrev_b32_e32 v130, 16, v112
	v_and_b32_e32 v131, 0xffff0000, v112
	v_lshlrev_b32_e32 v132, 16, v113
	v_and_b32_e32 v133, 0xffff0000, v113
	v_mul_f32_e32 v46, v66, v46
	v_mul_f32_e32 v47, v66, v47
	v_mul_f32_e32 v48, v66, v48
	v_mul_f32_e32 v49, v66, v49
	v_mul_f32_e32 v46, v46, v130
	v_mul_f32_e32 v47, v47, v131
	v_mul_f32_e32 v48, v48, v132
	v_mul_f32_e32 v49, v49, v133
	v_cvt_pk_bf16_f32 v46, v46, v47
	v_cvt_pk_bf16_f32 v47, v48, v49
	global_store_dwordx2 v[68:69], v[46:47], off offset:112
	s_waitcnt vmcnt(15)
	v_lshlrev_b32_e32 v130, 16, v114
	v_and_b32_e32 v131, 0xffff0000, v114
	v_lshlrev_b32_e32 v132, 16, v115
	v_and_b32_e32 v133, 0xffff0000, v115
	v_mul_f32_e32 v18, v66, v18
	v_mul_f32_e32 v19, v66, v19
	v_mul_f32_e32 v20, v66, v20
	v_mul_f32_e32 v21, v66, v21
	v_mul_f32_e32 v18, v18, v130
	v_mul_f32_e32 v19, v19, v131
	v_mul_f32_e32 v20, v20, v132
	v_mul_f32_e32 v21, v21, v133
	v_cvt_pk_bf16_f32 v18, v18, v19
	v_cvt_pk_bf16_f32 v19, v20, v21
	global_store_dwordx2 v[68:69], v[18:19], off offset:128
	s_waitcnt vmcnt(15)
	v_lshlrev_b32_e32 v130, 16, v116
	v_and_b32_e32 v131, 0xffff0000, v116
	v_lshlrev_b32_e32 v132, 16, v117
	v_and_b32_e32 v133, 0xffff0000, v117
	v_mul_f32_e32 v22, v66, v22
	v_mul_f32_e32 v23, v66, v23
	v_mul_f32_e32 v24, v66, v24
	v_mul_f32_e32 v25, v66, v25
	v_mul_f32_e32 v22, v22, v130
	v_mul_f32_e32 v23, v23, v131
	v_mul_f32_e32 v24, v24, v132
	v_mul_f32_e32 v25, v25, v133
	v_cvt_pk_bf16_f32 v22, v22, v23
	v_cvt_pk_bf16_f32 v23, v24, v25
	global_store_dwordx2 v[68:69], v[22:23], off offset:144
	s_waitcnt vmcnt(15)
	v_lshlrev_b32_e32 v130, 16, v118
	v_and_b32_e32 v131, 0xffff0000, v118
	v_lshlrev_b32_e32 v132, 16, v119
	v_and_b32_e32 v133, 0xffff0000, v119
	v_mul_f32_e32 v26, v66, v26
	v_mul_f32_e32 v27, v66, v27
	v_mul_f32_e32 v28, v66, v28
	v_mul_f32_e32 v29, v66, v29
	v_mul_f32_e32 v26, v26, v130
	v_mul_f32_e32 v27, v27, v131
	v_mul_f32_e32 v28, v28, v132
	v_mul_f32_e32 v29, v29, v133
	v_cvt_pk_bf16_f32 v26, v26, v27
	v_cvt_pk_bf16_f32 v27, v28, v29
	global_store_dwordx2 v[68:69], v[26:27], off offset:160
	s_waitcnt vmcnt(15)
	v_lshlrev_b32_e32 v130, 16, v120
	v_and_b32_e32 v131, 0xffff0000, v120
	v_lshlrev_b32_e32 v132, 16, v121
	v_and_b32_e32 v133, 0xffff0000, v121
	v_mul_f32_e32 v30, v66, v30
	v_mul_f32_e32 v31, v66, v31
	v_mul_f32_e32 v32, v66, v32
	v_mul_f32_e32 v33, v66, v33
	v_mul_f32_e32 v30, v30, v130
	v_mul_f32_e32 v31, v31, v131
	v_mul_f32_e32 v32, v32, v132
	v_mul_f32_e32 v33, v33, v133
	v_cvt_pk_bf16_f32 v30, v30, v31
	v_cvt_pk_bf16_f32 v31, v32, v33
	global_store_dwordx2 v[68:69], v[30:31], off offset:176
	s_waitcnt vmcnt(15)
	v_lshlrev_b32_e32 v130, 16, v122
	v_and_b32_e32 v131, 0xffff0000, v122
	v_lshlrev_b32_e32 v132, 16, v123
	v_and_b32_e32 v133, 0xffff0000, v123
	v_mul_f32_e32 v2, v66, v2
	v_mul_f32_e32 v3, v66, v3
	v_mul_f32_e32 v4, v66, v4
	v_mul_f32_e32 v5, v66, v5
	v_mul_f32_e32 v2, v2, v130
	v_mul_f32_e32 v3, v3, v131
	v_mul_f32_e32 v4, v4, v132
	v_mul_f32_e32 v5, v5, v133
	v_cvt_pk_bf16_f32 v2, v2, v3
	v_cvt_pk_bf16_f32 v3, v4, v5
	global_store_dwordx2 v[68:69], v[2:3], off offset:192
	s_waitcnt vmcnt(15)
	v_lshlrev_b32_e32 v130, 16, v124
	v_and_b32_e32 v131, 0xffff0000, v124
	v_lshlrev_b32_e32 v132, 16, v125
	v_and_b32_e32 v133, 0xffff0000, v125
	v_mul_f32_e32 v6, v66, v6
	v_mul_f32_e32 v7, v66, v7
	v_mul_f32_e32 v8, v66, v8
	v_mul_f32_e32 v9, v66, v9
	v_mul_f32_e32 v6, v6, v130
	v_mul_f32_e32 v7, v7, v131
	v_mul_f32_e32 v8, v8, v132
	v_mul_f32_e32 v9, v9, v133
	v_cvt_pk_bf16_f32 v6, v6, v7
	v_cvt_pk_bf16_f32 v7, v8, v9
	global_store_dwordx2 v[68:69], v[6:7], off offset:208
	s_waitcnt vmcnt(15)
	v_lshlrev_b32_e32 v130, 16, v126
	v_and_b32_e32 v131, 0xffff0000, v126
	v_lshlrev_b32_e32 v132, 16, v127
	v_and_b32_e32 v133, 0xffff0000, v127
	v_mul_f32_e32 v10, v66, v10
	v_mul_f32_e32 v11, v66, v11
	v_mul_f32_e32 v12, v66, v12
	v_mul_f32_e32 v13, v66, v13
	v_mul_f32_e32 v10, v10, v130
	v_mul_f32_e32 v11, v11, v131
	v_mul_f32_e32 v12, v12, v132
	v_mul_f32_e32 v13, v13, v133
	v_cvt_pk_bf16_f32 v10, v10, v11
	v_cvt_pk_bf16_f32 v11, v12, v13
	global_store_dwordx2 v[68:69], v[10:11], off offset:224
	s_waitcnt vmcnt(15)
	v_lshlrev_b32_e32 v130, 16, v128
	v_and_b32_e32 v131, 0xffff0000, v128
	v_lshlrev_b32_e32 v132, 16, v129
	v_and_b32_e32 v133, 0xffff0000, v129
	v_mul_f32_e32 v14, v66, v14
	v_mul_f32_e32 v15, v66, v15
	v_mul_f32_e32 v16, v66, v16
	v_mul_f32_e32 v17, v66, v17
	v_mul_f32_e32 v14, v14, v130
	v_mul_f32_e32 v15, v15, v131
	v_mul_f32_e32 v16, v16, v132
	v_mul_f32_e32 v17, v17, v133
	v_cvt_pk_bf16_f32 v14, v14, v15
	v_cvt_pk_bf16_f32 v15, v16, v17
	global_store_dwordx2 v[68:69], v[14:15], off offset:240

.LBB0_348:
	v_readlane_b32 s6, v254, 22
	s_add_i32 s64, s6, s36
	v_mbcnt_lo_u32_b32 v11, -1, 0
	v_mbcnt_hi_u32_b32 v11, -1, v11
	s_add_i32 s64, s64, 16
	v_and_b32_e32 v167, 31, v11
	v_add_u32_e32 v166, s64, v167
	v_min_i32_e32 v2, 0x80f, v166
	v_ashrrev_i32_e32 v3, 31, v2
	v_lshl_add_u64 v[2:3], s[10:11], 0, v[2:3]
	v_mov_b64_e32 v[4:5], s[50:51]
	v_mad_u64_u32 v[4:5], s[6:7], v2, s58, v[4:5]
	v_bfe_u32 v10, v11, 5, 1
	v_mad_i32_i24 v5, v3, s58, v5
	s_mov_b32 s15, s45
	v_lshl_add_u64 v[4:5], v[4:5], 0, s[14:15]
	s_waitcnt lgkmcnt(0)
	v_lshlrev_b32_e32 v0, 4, v10
	v_lshl_add_u64 v[4:5], v[4:5], 0, v[0:1]
	v_readlane_b32 s6, v253, 15
	global_load_dwordx4 v[98:101], v[4:5], off
	global_load_dwordx4 v[102:105], v[4:5], off offset:32
	global_load_dwordx4 v[106:109], v[4:5], off offset:64
	global_load_dwordx4 v[110:113], v[4:5], off offset:96
	global_load_dwordx4 v[114:117], v[4:5], off offset:128
	global_load_dwordx4 v[118:121], v[4:5], off offset:160
	global_load_dwordx4 v[122:125], v[4:5], off offset:192
	global_load_dwordx4 v[126:129], v[4:5], off offset:224
	global_load_dwordx4 v[130:133], v[4:5], off offset:256
	global_load_dwordx4 v[134:137], v[4:5], off offset:288
	global_load_dwordx4 v[138:141], v[4:5], off offset:320
	global_load_dwordx4 v[142:145], v[4:5], off offset:352
	v_add_u32_e32 v4, s6, v11
	v_readlane_b32 s6, v254, 48
	v_lshlrev_b64 v[2:3], 5, v[2:3]
	v_readlane_b32 s7, v254, 49
	s_lshl_b32 s16, s34, 1
	s_mov_b32 s17, s45
	v_lshl_add_u64 v[2:3], s[6:7], 0, v[2:3]
	v_lshl_add_u64 v[6:7], v[2:3], 0, s[44:45]
	v_ashrrev_i32_e32 v2, 4, v4
	v_ashrrev_i32_e32 v3, 31, v2
	v_lshl_add_u64 v[8:9], s[10:11], 0, v[2:3]
	v_lshlrev_b64 v[8:9], 11, v[8:9]
	v_lshl_add_u64 v[8:9], s[66:67], 0, v[8:9]
	v_lshlrev_b32_e32 v5, 4, v4
	v_lshl_add_u64 v[8:9], v[8:9], 0, s[16:17]
	v_and_b32_e32 v168, 0xf0, v5
	v_mov_b32_e32 v169, v1
	v_add_u32_e32 v12, 0x200, v4
	v_lshl_add_u64 v[8:9], v[8:9], 0, v[168:169]
	global_load_dword v13, v[6:7], off
	global_load_dwordx4 v[146:149], v[8:9], off
	v_ashrrev_i32_e32 v6, 4, v12
	v_ashrrev_i32_e32 v7, 31, v6
	v_lshl_add_u64 v[8:9], s[10:11], 0, v[6:7]
	v_lshlrev_b64 v[8:9], 11, v[8:9]
	v_lshl_add_u64 v[8:9], s[66:67], 0, v[8:9]
	v_lshl_add_u64 v[8:9], v[8:9], 0, s[16:17]
	v_lshl_add_u64 v[14:15], v[8:9], 0, v[168:169]
	v_ashrrev_i32_e32 v8, 3, v4
	v_ashrrev_i32_e32 v9, 31, v8
	v_lshl_add_u64 v[16:17], s[10:11], 0, v[8:9]
	v_readlane_b32 s6, v254, 24
	v_lshlrev_b64 v[16:17], 7, v[16:17]
	v_readlane_b32 s7, v254, 25
	v_and_b32_e32 v170, 0x70, v5
	v_mov_b32_e32 v171, v1
	v_lshl_add_u64 v[16:17], s[6:7], 0, v[16:17]
	v_readlane_b32 s6, v254, 26
	v_readlane_b32 s7, v254, 27
	v_lshl_add_u64 v[16:17], v[16:17], 0, v[170:171]
	global_load_dwordx4 v[150:153], v[14:15], off
	global_load_dwordx4 v[154:157], v[16:17], off
	v_add_u32_e32 v5, s34, v8
	v_mov_b64_e32 v[14:15], s[6:7]
	v_ashrrev_i32_e32 v12, 3, v12
	v_mad_i64_i32 v[16:17], s[6:7], v5, s85, v[14:15]
	v_add_u32_e32 v5, s34, v12
	v_lshl_add_u64 v[16:17], v[16:17], 0, s[12:13]
	v_mad_i64_i32 v[14:15], s[6:7], v5, s85, v[14:15]
	v_lshl_add_u64 v[16:17], v[16:17], 0, v[170:171]
	v_lshl_add_u64 v[14:15], v[14:15], 0, s[12:13]
	v_lshl_add_u64 v[14:15], v[14:15], 0, v[170:171]
	global_load_dwordx4 v[158:161], v[16:17], off
	global_load_dwordx4 v[162:165], v[14:15], off
	v_cmp_lt_i32_e32 vcc, 63, v4
	v_cmp_gt_i32_e64 s[6:7], 64, v4
	v_mov_b32_e32 v169, 0
	v_ashrrev_i32_e32 v5, 31, v4
	v_mov_b32_e32 v171, 0
	s_and_saveexec_b64 s[28:29], s[6:7]
	s_cbranch_execz .LBB0_350
	v_readlane_b32 s40, v254, 28
	v_lshl_add_u64 v[14:15], s[10:11], 0, v[4:5]
	v_readlane_b32 s41, v254, 29
	s_nop 1
	v_lshl_add_u64 v[16:17], v[14:15], 2, s[40:41]
	v_readlane_b32 s40, v254, 52
	v_lshlrev_b64 v[14:15], 5, v[14:15]
	v_readlane_b32 s41, v254, 53
	s_nop 1
	v_lshl_add_u64 v[14:15], s[40:41], 0, v[14:15]
	v_lshl_add_u64 v[14:15], v[14:15], 0, s[44:45]
	global_load_dword v171, v[14:15], off
	global_load_dword v169, v[16:17], off

.LBB0_371:
	s_and_b64 vcc, exec, s[94:95]
	s_cbranch_vccz .LBB0_318
	ds_bpermute_b32 v0, v211, v216
	v_readlane_b32 s4, v254, 22
	s_nop 1
	v_or_b32_e32 v66, s4, v167
	s_movk_i32 s4, 0x100
	v_cmp_gt_i32_e32 vcc, s4, v66
	s_and_b64 s[6:7], s[2:3], vcc
	s_and_saveexec_b64 s[4:5], s[6:7]
	s_cbranch_execz .LBB0_317
	s_waitcnt lgkmcnt(0)
	v_add_f32_e32 v0, v216, v0
	v_div_scale_f32 v66, s[6:7], v0, v0, 1.0
	v_rcp_f32_e32 v67, v66
	v_ashrrev_i32_e32 v167, 31, v166
	v_readlane_b32 s6, v252, 43
	v_readlane_b32 s7, v252, 44
	v_fma_f32 v68, -v66, v67, 1.0
	v_fmac_f32_e32 v67, v68, v67
	v_div_scale_f32 v68, vcc, 1.0, v0, 1.0
	v_mul_f32_e32 v69, v68, v67
	v_fma_f32 v70, -v66, v69, v68
	v_fmac_f32_e32 v69, v70, v67
	v_fma_f32 v66, -v66, v69, v68
	v_div_fmas_f32 v66, v66, v67, v69
	v_lshl_add_u64 v[68:69], s[10:11], 0, v[166:167]
	v_lshlrev_b64 v[68:69], 11, v[68:69]
	v_lshl_add_u64 v[68:69], s[6:7], 0, v[68:69]
	s_mov_b32 s17, s45
	v_div_fixup_f32 v66, v66, v0, 1.0
	v_lshl_add_u64 v[68:69], v[68:69], 0, s[16:17]
	v_lshlrev_b32_e32 v0, 1, v208
	v_lshl_add_u64 v[68:69], v[68:69], 0, v[0:1]
	global_load_dwordx2 v[98:99], v[68:69], off
	global_load_dwordx2 v[100:101], v[68:69], off offset:16
	global_load_dwordx2 v[102:103], v[68:69], off offset:32
	global_load_dwordx2 v[104:105], v[68:69], off offset:48
	global_load_dwordx2 v[106:107], v[68:69], off offset:64
	global_load_dwordx2 v[108:109], v[68:69], off offset:80
	global_load_dwordx2 v[110:111], v[68:69], off offset:96
	global_load_dwordx2 v[112:113], v[68:69], off offset:112
	global_load_dwordx2 v[114:115], v[68:69], off offset:128
	global_load_dwordx2 v[116:117], v[68:69], off offset:144
	global_load_dwordx2 v[118:119], v[68:69], off offset:160
	global_load_dwordx2 v[120:121], v[68:69], off offset:176
	global_load_dwordx2 v[122:123], v[68:69], off offset:192
	global_load_dwordx2 v[124:125], v[68:69], off offset:208
	global_load_dwordx2 v[126:127], v[68:69], off offset:224
	global_load_dwordx2 v[128:129], v[68:69], off offset:240
	s_waitcnt vmcnt(15)
	v_lshlrev_b32_e32 v130, 16, v98
	v_and_b32_e32 v131, 0xffff0000, v98
	v_lshlrev_b32_e32 v132, 16, v99
	v_and_b32_e32 v133, 0xffff0000, v99
	v_mul_f32_e32 v50, v66, v50
	v_mul_f32_e32 v51, v66, v51
	v_mul_f32_e32 v52, v66, v52
	v_mul_f32_e32 v53, v66, v53
	v_mul_f32_e32 v50, v50, v130
	v_mul_f32_e32 v51, v51, v131
	v_mul_f32_e32 v52, v52, v132
	v_mul_f32_e32 v53, v53, v133
	v_cvt_pk_bf16_f32 v50, v50, v51
	v_cvt_pk_bf16_f32 v51, v52, v53
	global_store_dwordx2 v[68:69], v[50:51], off
	s_waitcnt vmcnt(15)
	v_lshlrev_b32_e32 v130, 16, v100
	v_and_b32_e32 v131, 0xffff0000, v100
	v_lshlrev_b32_e32 v132, 16, v101
	v_and_b32_e32 v133, 0xffff0000, v101
	v_mul_f32_e32 v54, v66, v54
	v_mul_f32_e32 v55, v66, v55
	v_mul_f32_e32 v56, v66, v56
	v_mul_f32_e32 v57, v66, v57
	v_mul_f32_e32 v54, v54, v130
	v_mul_f32_e32 v55, v55, v131
	v_mul_f32_e32 v56, v56, v132
	v_mul_f32_e32 v57, v57, v133
	v_cvt_pk_bf16_f32 v54, v54, v55
	v_cvt_pk_bf16_f32 v55, v56, v57
	global_store_dwordx2 v[68:69], v[54:55], off offset:16
	s_waitcnt vmcnt(15)
	v_lshlrev_b32_e32 v130, 16, v102
	v_and_b32_e32 v131, 0xffff0000, v102
	v_lshlrev_b32_e32 v132, 16, v103
	v_and_b32_e32 v133, 0xffff0000, v103
	v_mul_f32_e32 v58, v66, v58
	v_mul_f32_e32 v59, v66, v59
	v_mul_f32_e32 v60, v66, v60
	v_mul_f32_e32 v61, v66, v61
	v_mul_f32_e32 v58, v58, v130
	v_mul_f32_e32 v59, v59, v131
	v_mul_f32_e32 v60, v60, v132
	v_mul_f32_e32 v61, v61, v133
	v_cvt_pk_bf16_f32 v58, v58, v59
	v_cvt_pk_bf16_f32 v59, v60, v61
	global_store_dwordx2 v[68:69], v[58:59], off offset:32
	s_waitcnt vmcnt(15)
	v_lshlrev_b32_e32 v130, 16, v104
	v_and_b32_e32 v131, 0xffff0000, v104
	v_lshlrev_b32_e32 v132, 16, v105
	v_and_b32_e32 v133, 0xffff0000, v105
	v_mul_f32_e32 v62, v66, v62
	v_mul_f32_e32 v63, v66, v63
	v_mul_f32_e32 v64, v66, v64
	v_mul_f32_e32 v65, v66, v65
	v_mul_f32_e32 v62, v62, v130
	v_mul_f32_e32 v63, v63, v131
	v_mul_f32_e32 v64, v64, v132
	v_mul_f32_e32 v65, v65, v133
	v_cvt_pk_bf16_f32 v62, v62, v63
	v_cvt_pk_bf16_f32 v63, v64, v65
	global_store_dwordx2 v[68:69], v[62:63], off offset:48
	s_waitcnt vmcnt(15)
	v_lshlrev_b32_e32 v130, 16, v106
	v_and_b32_e32 v131, 0xffff0000, v106
	v_lshlrev_b32_e32 v132, 16, v107
	v_and_b32_e32 v133, 0xffff0000, v107
	v_mul_f32_e32 v34, v66, v34
	v_mul_f32_e32 v35, v66, v35
	v_mul_f32_e32 v36, v66, v36
	v_mul_f32_e32 v37, v66, v37
	v_mul_f32_e32 v34, v34, v130
	v_mul_f32_e32 v35, v35, v131
	v_mul_f32_e32 v36, v36, v132
	v_mul_f32_e32 v37, v37, v133
	v_cvt_pk_bf16_f32 v34, v34, v35
	v_cvt_pk_bf16_f32 v35, v36, v37
	global_store_dwordx2 v[68:69], v[34:35], off offset:64
	s_waitcnt vmcnt(15)
	v_lshlrev_b32_e32 v130, 16, v108
	v_and_b32_e32 v131, 0xffff0000, v108
	v_lshlrev_b32_e32 v132, 16, v109
	v_and_b32_e32 v133, 0xffff0000, v109
	v_mul_f32_e32 v38, v66, v38
	v_mul_f32_e32 v39, v66, v39
	v_mul_f32_e32 v40, v66, v40
	v_mul_f32_e32 v41, v66, v41
	v_mul_f32_e32 v38, v38, v130
	v_mul_f32_e32 v39, v39, v131
	v_mul_f32_e32 v40, v40, v132
	v_mul_f32_e32 v41, v41, v133
	v_cvt_pk_bf16_f32 v38, v38, v39
	v_cvt_pk_bf16_f32 v39, v40, v41
	global_store_dwordx2 v[68:69], v[38:39], off offset:80
	s_waitcnt vmcnt(15)
	v_lshlrev_b32_e32 v130, 16, v110
	v_and_b32_e32 v131, 0xffff0000, v110
	v_lshlrev_b32_e32 v132, 16, v111
	v_and_b32_e32 v133, 0xffff0000, v111
	v_mul_f32_e32 v42, v66, v42
	v_mul_f32_e32 v43, v66, v43
	v_mul_f32_e32 v44, v66, v44
	v_mul_f32_e32 v45, v66, v45
	v_mul_f32_e32 v42, v42, v130
	v_mul_f32_e32 v43, v43, v131
	v_mul_f32_e32 v44, v44, v132
	v_mul_f32_e32 v45, v45, v133
	v_cvt_pk_bf16_f32 v42, v42, v43
	v_cvt_pk_bf16_f32 v43, v44, v45
	global_store_dwordx2 v[68:69], v[42:43], off offset:96
	s_waitcnt vmcnt(15)
	v_lshlrev_b32_e32 v130, 16, v112
	v_and_b32_e32 v131, 0xffff0000, v112
	v_lshlrev_b32_e32 v132, 16, v113
	v_and_b32_e32 v133, 0xffff0000, v113
	v_mul_f32_e32 v46, v66, v46
	v_mul_f32_e32 v47, v66, v47
	v_mul_f32_e32 v48, v66, v48
	v_mul_f32_e32 v49, v66, v49
	v_mul_f32_e32 v46, v46, v130
	v_mul_f32_e32 v47, v47, v131
	v_mul_f32_e32 v48, v48, v132
	v_mul_f32_e32 v49, v49, v133
	v_cvt_pk_bf16_f32 v46, v46, v47
	v_cvt_pk_bf16_f32 v47, v48, v49
	global_store_dwordx2 v[68:69], v[46:47], off offset:112
	s_waitcnt vmcnt(15)
	v_lshlrev_b32_e32 v130, 16, v114
	v_and_b32_e32 v131, 0xffff0000, v114
	v_lshlrev_b32_e32 v132, 16, v115
	v_and_b32_e32 v133, 0xffff0000, v115
	v_mul_f32_e32 v18, v66, v18
	v_mul_f32_e32 v19, v66, v19
	v_mul_f32_e32 v20, v66, v20
	v_mul_f32_e32 v21, v66, v21
	v_mul_f32_e32 v18, v18, v130
	v_mul_f32_e32 v19, v19, v131
	v_mul_f32_e32 v20, v20, v132
	v_mul_f32_e32 v21, v21, v133
	v_cvt_pk_bf16_f32 v18, v18, v19
	v_cvt_pk_bf16_f32 v19, v20, v21
	global_store_dwordx2 v[68:69], v[18:19], off offset:128
	s_waitcnt vmcnt(15)
	v_lshlrev_b32_e32 v130, 16, v116
	v_and_b32_e32 v131, 0xffff0000, v116
	v_lshlrev_b32_e32 v132, 16, v117
	v_and_b32_e32 v133, 0xffff0000, v117
	v_mul_f32_e32 v22, v66, v22
	v_mul_f32_e32 v23, v66, v23
	v_mul_f32_e32 v24, v66, v24
	v_mul_f32_e32 v25, v66, v25
	v_mul_f32_e32 v22, v22, v130
	v_mul_f32_e32 v23, v23, v131
	v_mul_f32_e32 v24, v24, v132
	v_mul_f32_e32 v25, v25, v133
	v_cvt_pk_bf16_f32 v22, v22, v23
	v_cvt_pk_bf16_f32 v23, v24, v25
	global_store_dwordx2 v[68:69], v[22:23], off offset:144
	s_waitcnt vmcnt(15)
	v_lshlrev_b32_e32 v130, 16, v118
	v_and_b32_e32 v131, 0xffff0000, v118
	v_lshlrev_b32_e32 v132, 16, v119
	v_and_b32_e32 v133, 0xffff0000, v119
	v_mul_f32_e32 v26, v66, v26
	v_mul_f32_e32 v27, v66, v27
	v_mul_f32_e32 v28, v66, v28
	v_mul_f32_e32 v29, v66, v29
	v_mul_f32_e32 v26, v26, v130
	v_mul_f32_e32 v27, v27, v131
	v_mul_f32_e32 v28, v28, v132
	v_mul_f32_e32 v29, v29, v133
	v_cvt_pk_bf16_f32 v26, v26, v27
	v_cvt_pk_bf16_f32 v27, v28, v29
	global_store_dwordx2 v[68:69], v[26:27], off offset:160
	s_waitcnt vmcnt(15)
	v_lshlrev_b32_e32 v130, 16, v120
	v_and_b32_e32 v131, 0xffff0000, v120
	v_lshlrev_b32_e32 v132, 16, v121
	v_and_b32_e32 v133, 0xffff0000, v121
	v_mul_f32_e32 v30, v66, v30
	v_mul_f32_e32 v31, v66, v31
	v_mul_f32_e32 v32, v66, v32
	v_mul_f32_e32 v33, v66, v33
	v_mul_f32_e32 v30, v30, v130
	v_mul_f32_e32 v31, v31, v131
	v_mul_f32_e32 v32, v32, v132
	v_mul_f32_e32 v33, v33, v133
	v_cvt_pk_bf16_f32 v30, v30, v31
	v_cvt_pk_bf16_f32 v31, v32, v33
	global_store_dwordx2 v[68:69], v[30:31], off offset:176
	s_waitcnt vmcnt(15)
	v_lshlrev_b32_e32 v130, 16, v122
	v_and_b32_e32 v131, 0xffff0000, v122
	v_lshlrev_b32_e32 v132, 16, v123
	v_and_b32_e32 v133, 0xffff0000, v123
	v_mul_f32_e32 v2, v66, v2
	v_mul_f32_e32 v3, v66, v3
	v_mul_f32_e32 v4, v66, v4
	v_mul_f32_e32 v5, v66, v5
	v_mul_f32_e32 v2, v2, v130
	v_mul_f32_e32 v3, v3, v131
	v_mul_f32_e32 v4, v4, v132
	v_mul_f32_e32 v5, v5, v133
	v_cvt_pk_bf16_f32 v2, v2, v3
	v_cvt_pk_bf16_f32 v3, v4, v5
	global_store_dwordx2 v[68:69], v[2:3], off offset:192
	s_waitcnt vmcnt(15)
	v_lshlrev_b32_e32 v130, 16, v124
	v_and_b32_e32 v131, 0xffff0000, v124
	v_lshlrev_b32_e32 v132, 16, v125
	v_and_b32_e32 v133, 0xffff0000, v125
	v_mul_f32_e32 v6, v66, v6
	v_mul_f32_e32 v7, v66, v7
	v_mul_f32_e32 v8, v66, v8
	v_mul_f32_e32 v9, v66, v9
	v_mul_f32_e32 v6, v6, v130
	v_mul_f32_e32 v7, v7, v131
	v_mul_f32_e32 v8, v8, v132
	v_mul_f32_e32 v9, v9, v133
	v_cvt_pk_bf16_f32 v6, v6, v7
	v_cvt_pk_bf16_f32 v7, v8, v9
	global_store_dwordx2 v[68:69], v[6:7], off offset:208
	s_waitcnt vmcnt(15)
	v_lshlrev_b32_e32 v130, 16, v126
	v_and_b32_e32 v131, 0xffff0000, v126
	v_lshlrev_b32_e32 v132, 16, v127
	v_and_b32_e32 v133, 0xffff0000, v127
	v_mul_f32_e32 v10, v66, v10
	v_mul_f32_e32 v11, v66, v11
	v_mul_f32_e32 v12, v66, v12
	v_mul_f32_e32 v13, v66, v13
	v_mul_f32_e32 v10, v10, v130
	v_mul_f32_e32 v11, v11, v131
	v_mul_f32_e32 v12, v12, v132
	v_mul_f32_e32 v13, v13, v133
	v_cvt_pk_bf16_f32 v10, v10, v11
	v_cvt_pk_bf16_f32 v11, v12, v13
	global_store_dwordx2 v[68:69], v[10:11], off offset:224
	s_waitcnt vmcnt(15)
	v_lshlrev_b32_e32 v130, 16, v128
	v_and_b32_e32 v131, 0xffff0000, v128
	v_lshlrev_b32_e32 v132, 16, v129
	v_and_b32_e32 v133, 0xffff0000, v129
	v_mul_f32_e32 v14, v66, v14
	v_mul_f32_e32 v15, v66, v15
	v_mul_f32_e32 v16, v66, v16
	v_mul_f32_e32 v17, v66, v17
	v_mul_f32_e32 v14, v14, v130
	v_mul_f32_e32 v15, v15, v131
	v_mul_f32_e32 v16, v16, v132
	v_mul_f32_e32 v17, v17, v133
	v_cvt_pk_bf16_f32 v14, v14, v15
	v_cvt_pk_bf16_f32 v15, v16, v17
	global_store_dwordx2 v[68:69], v[14:15], off offset:240
	s_branch .LBB0_317
